# v097 + P10: first row group of the second u-sweep fetched during the last iteration of the first (in place of the dummy loads); scalar code between the sweeps re-registered off buffer A
# speedup vs baseline: 1.0063x; 1.0063x over previous
; #define PU_LOAD(BUF, EV, S0) do { _Pragma("unroll") for (int i = 0; i < 8; ++i) { const int row_ = __builtin_amdgcn_readlane(EV, (S0) + i); BUF[i & 3][i >> 2] = *(const u32x4*)(PU8 + (size_t)row_ * 1024 + lane * 16); } } while (0)
; __global__ void __launch_bounds__(NT, 2) mk_fwd(Args args) {
;     ...
;             float act0 = 0.f, act1 = 0.f;
;             u32x4 bA[4][2], bB[4][2];
; #pragma unroll
;             for (int hh = 0; hh < 2; ++hh) {
;                 const int ev = hh ? e1 : e0; const float gv = hh ? g1 : g0; float dv = 0.f;
;                 PU_LOAD(bA, ev, 0);
; #pragma unroll 1
;                 for (int s = 0; s < 64; s += 16) {
;                     PU_LOAD(bB, ev, s + 8);
;                     PU_DOT4(bA, 0, s); PU_DOT4(bA, 1, s + 4);
;                     if (s + 16 < 64) PU_LOAD(bA, ev, s + 16);
.Lp10_dmy_889:
	v_readlane_b32 s30, v106, 0
	s_ashr_i32 s31, s30, 31
	s_lshl_b64 s[30:31], s[30:31], 10
	v_lshl_add_u64 v[228:229], v[98:99], 0, s[30:31]
	global_load_dwordx4 v[0:3], v[228:229], off
	v_readlane_b32 s30, v106, 1
	s_ashr_i32 s31, s30, 31
	s_lshl_b64 s[30:31], s[30:31], 10
	v_lshl_add_u64 v[230:231], v[98:99], 0, s[30:31]
	global_load_dwordx4 v[4:7], v[230:231], off
	v_readlane_b32 s30, v106, 2
	s_ashr_i32 s31, s30, 31
	s_lshl_b64 s[30:31], s[30:31], 10
	v_lshl_add_u64 v[232:233], v[98:99], 0, s[30:31]
	global_load_dwordx4 v[8:11], v[232:233], off
	v_readlane_b32 s30, v106, 3
	s_ashr_i32 s31, s30, 31
	s_lshl_b64 s[30:31], s[30:31], 10
	v_lshl_add_u64 v[234:235], v[98:99], 0, s[30:31]
	global_load_dwordx4 v[12:15], v[234:235], off
	v_readlane_b32 s30, v106, 4
	s_ashr_i32 s31, s30, 31
	s_lshl_b64 s[30:31], s[30:31], 10
	v_lshl_add_u64 v[228:229], v[98:99], 0, s[30:31]
	global_load_dwordx4 v[16:19], v[228:229], off
	v_readlane_b32 s30, v106, 5
	s_ashr_i32 s31, s30, 31
	s_lshl_b64 s[30:31], s[30:31], 10
	v_lshl_add_u64 v[230:231], v[98:99], 0, s[30:31]
	global_load_dwordx4 v[20:23], v[230:231], off
	v_readlane_b32 s30, v106, 6
	s_ashr_i32 s31, s30, 31
	s_lshl_b64 s[30:31], s[30:31], 10
	v_lshl_add_u64 v[232:233], v[98:99], 0, s[30:31]
	global_load_dwordx4 v[24:27], v[232:233], off
	v_readlane_b32 s30, v106, 7
	s_ashr_i32 s31, s30, 31
	s_lshl_b64 s[30:31], s[30:31], 10
	v_lshl_add_u64 v[234:235], v[98:99], 0, s[30:31]
	global_load_dwordx4 v[28:31], v[234:235], off

; __device__ __forceinline__ float gelu1(float x) { return 0.5f * x * (1.0f + erff(x * 0.70710678118654752f)); }
; __global__ void __launch_bounds__(NT, 2) mk_fwd(Args args) {
;     ...
;                 const float d = dv * SCL[ev];
;                 const float a = gelu1(d) * gv * SCL[16384 + ev];
.LBB0_891:
	v_ashrrev_i32_e32 v109, 31, v108
	v_lshl_add_u64 v[236:237], v[108:109], 2, s[6:7]
	v_mov_b32_e32 v238, v218
	v_mul_f32_e32 v111, v107, v238
	v_mul_f32_e32 v112, 0x3f3504f3, v111
	v_cmp_nlt_f32_e64 s[4:5], |v112|, 1.0
	s_and_saveexec_b64 s[30:31], s[4:5]
	s_xor_b64 s[4:5], exec, s[30:31]
	s_cbranch_execz .LBB0_893
	v_fma_f32 v238, |v112|, s11, v154
	v_fma_f32 v238, |v112|, v238, s13
	v_fma_f32 v238, |v112|, v238, s15
	v_fma_f32 v238, |v112|, v238, s17
	v_fma_f32 v238, |v112|, v238, s19
	v_fma_f32 v238, |v112|, v238, s21
	v_fma_f32 v238, |v112|, v238, |v112|
	v_mul_f32_e32 v239, 0xbfb8aa3b, v238
	v_fma_f32 v240, v238, s23, -v239
	v_rndne_f32_e32 v241, v239
	v_fmac_f32_e32 v240, 0xb2a5705f, v238
	v_sub_f32_e32 v239, v239, v241
	v_add_f32_e32 v239, v239, v240
	v_cvt_i32_f32_e32 v240, v241
	v_exp_f32_e32 v239, v239
	v_cmp_nlt_f32_e32 vcc, s25, v238
	v_ldexp_f32 v239, v239, v240
	s_nop 0
	v_cndmask_b32_e32 v239, 0, v239, vcc
	v_cmp_ngt_f32_e32 vcc, s26, v238
	s_nop 1
	v_cndmask_b32_e32 v238, v155, v239, vcc
	v_sub_f32_e32 v113, 1.0, v238
.LBB0_893:
	s_andn2_saveexec_b64 s[4:5], s[4:5]
	v_mul_f32_e32 v238, v112, v112
	v_fmamk_f32 v239, v238, 0xba1345e1, v152
	v_fmaak_f32 v239, v238, v239, 0xbcdac9b8
	v_fmaak_f32 v239, v238, v239, 0x3de703be
	v_fmaak_f32 v239, v238, v239, 0xbec09330
	v_fmaak_f32 v238, v238, v239, 0x3e0375d0
	v_fma_f32 v113, |v112|, v238, |v112|
	s_or_b64 exec, exec, s[4:5]
	v_add_co_u32_e32 v240, vcc, 0x10000, v236
	s_nop 0
	v_addc_co_u32_e32 v241, vcc, 0, v237, vcc
	global_load_dword v114, v[240:241], off
	s_mov_b32 s10, 0
	v_mov_b32_e32 v109, 0
